# one of the two co-resident workgroups (HW_ID TG_ID bit0) runs the P2/P5/P7 GEMM phases at s_setprio 1
# speedup vs baseline: 1.0581x; 1.0028x over previous
; DI void phase2(const Params& p, char* smem, int rep) {
;   const u16* H = (const u16*)(p.ws + WS_H); const u16* W = (const u16*)(p.ws + WS_WINT); u16* P = (u16*)(p.ws + WS_P); float* SSQ = (float*)(p.ws + WS_SSQ);
;   (void)rep;
;   for (int it = blockIdx.x; it < 64 * 32; it += gridDim.x) {
;     const int tn = it / 64, tm = it % 64;
.LBB0_382:
	s_getreg_b32 s98, hwreg(HW_REG_HW_ID, 16, 4)
	s_bitcmp0_b32 s98, 0
	s_cbranch_scc1 .Lprio_p2
	s_setprio 1

; template <class BG>
; DI void xcd_barrier_bg(const XcdBarrier b, char* smem, BG bg) {
;   asm volatile("s_waitcnt vmcnt(0)" ::: "memory");
;   __syncthreads();
;   volatile unsigned* sst = (volatile unsigned*)(smem + 12);
;   unsigned mygen = 0u;
;   if (threadIdx.x == 0) {
;     unsigned* bar = b.bar;
;     __builtin_amdgcn_s_waitcnt(0);
;     unsigned nloc = b.st[0], nx = b.st[1];
;     if (nloc == 0u) { xcd_barrier_complete(bar, b.x, nloc, nx); b.st[0] = nloc; b.st[1] = nx; }
.LBB0_398:
	s_setprio 0
	s_cmp_lt_i32 s38, 4
	s_cselect_b64 s[40:41], -1, 0
	s_cmp_gt_i32 s38, 3
	s_cselect_b64 s[2:3], -1, 0
	s_cmp_lt_i32 s39, 4
	s_cselect_b64 s[4:5], -1, 0
	s_or_b64 s[2:3], s[2:3], s[4:5]
	s_and_b64 vcc, exec, s[2:3]
	s_cbranch_vccnz .LBB0_535
	s_andn2_b64 vcc, exec, s[42:43]
	s_cbranch_vccnz .LBB0_491
	s_waitcnt vmcnt(0)
	v_mov_b32_e32 v1, 0
	v_cmp_eq_u32_e64 s[2:3], 0, v0
	s_waitcnt lgkmcnt(0)
	s_barrier
	s_and_saveexec_b64 s[42:43], s[2:3]
	s_cbranch_execz .LBB0_440
	v_mov_b32_e32 v1, 0
	s_waitcnt vmcnt(0) expcnt(0) lgkmcnt(0)
	ds_read_b32 v4, v1
	ds_read_b32 v2, v1 offset:4
	s_waitcnt lgkmcnt(1)
	v_cmp_ne_u32_e32 vcc, 0, v4
	s_cbranch_vccnz .LBB0_417
	s_load_dwordx2 s[4:5], s[0:1], 0xc0
	s_load_dword s8, s[0:1], 0xc8
	s_mov_b64 s[6:7], 0x1000
	s_waitcnt lgkmcnt(0)
	v_lshl_add_u64 v[2:3], v[188:189], 0, s[6:7]
	s_mov_b32 s24, 1
	s_mul_i32 s13, s5, s4
	s_mov_b64 s[4:5], 0x1100
	v_lshl_add_u64 v[4:5], v[188:189], 0, s[4:5]
	s_mov_b64 s[4:5], 0x1200
	v_lshl_add_u64 v[6:7], v[188:189], 0, s[4:5]
	s_mov_b64 s[4:5], 0x1300
	s_mul_i32 s13, s13, s8
	v_lshl_add_u64 v[8:9], v[188:189], 0, s[4:5]
	s_mov_b64 s[4:5], 0
	s_branch .LBB0_405

.LBB0_754:
	s_setprio 0
	s_cmp_lt_i32 s38, 7
	s_cselect_b64 s[42:43], -1, 0
	s_cmp_gt_i32 s38, 6
	s_cselect_b64 s[2:3], -1, 0
	s_cmp_lt_i32 s39, 7
	s_cselect_b64 s[4:5], -1, 0
	s_or_b64 s[2:3], s[2:3], s[4:5]
	s_and_b64 vcc, exec, s[2:3]
	s_cbranch_vccnz .LBB0_855
	s_andn2_b64 vcc, exec, s[40:41]
	s_cbranch_vccnz .LBB0_757
	s_cbranch_execz .LBB0_758
	s_branch .LBB0_849

; DI void phase7(const Params& p, char* smem) {
;   const u16* H2 = (const u16*)(p.ws + WS_H); const u16* W = (const u16*)(p.ws + WS_WQT); u16* PQ = (u16*)(p.ws + WS_P);
;   for (int it = blockIdx.x; it < 64 * 16; it += gridDim.x) {
;     const int tn = it / 64, tm = it % 64;
.LBB0_950:
.LBB0_951:
	s_getreg_b32 s98, hwreg(HW_REG_HW_ID, 16, 4)
	s_bitcmp0_b32 s98, 0
	s_cbranch_scc1 .Lprio_p7
	s_setprio 1

; __global__ void __launch_bounds__(256, 2) mega(Params p) {
;     ...
;   auto bg_unit = [&]() __attribute__((always_inline)) -> bool {
;     const int c = grab((unsigned*)(p.ws + WS_BAR) + CTR_BG, smem);
;     if (c >= BG_CHUNKS) return false;
; #pragma unroll 1
;     for (int i = 0; i < 2; ++i) {
;       const int item = c * 2 + i;
;       const bool isu = item < 4096;
;       conv_rows_item(isu ? p.in[17] : p.in[18], (unsigned char*)(p.ws + (isu ? WS_U : WS_V)), (float*)(p.ws + (isu ? WS_USC : WS_VSC)), isu ? item : item - 4096, isu);
;     }
;     return true;
;   };
.LBB0_961:
	s_setprio 0
	s_waitcnt lgkmcnt(0)
	v_and_b32_e32 v2, 63, v0
	v_lshlrev_b32_e32 v34, 4, v2
	v_cmp_eq_u32_e64 s[4:5], 0, v2
	v_mbcnt_lo_u32_b32 v2, -1, 0
	v_mbcnt_hi_u32_b32 v46, -1, v2
	s_mov_b64 s[14:15], src_shared_base
	s_add_u32 s16, s82, 0x3b00
	v_mov_b32_e32 v37, 0
	v_and_b32_e32 v2, 64, v46
	v_cmp_eq_u32_e64 s[2:3], 0, v0
	s_addc_u32 s17, s83, 0
	v_lshrrev_b32_e32 v1, 6, v0
	v_mov_b32_e32 v35, v37
	s_mov_b64 s[18:19], 0
	s_add_i32 s13, 0, 8
	s_movk_i32 s14, 0x1000
	s_movk_i32 s30, 0xfff
	s_mov_b64 s[20:21], 0x1000
	s_mov_b32 s31, 0x43c00000
	s_mov_b32 s34, 0x800000
	s_movk_i32 s35, 0xff9c
	s_mov_b32 s36, 0x42fe0000
	s_mov_b32 s37, 0x40c0c00
	v_add_u32_e32 v47, 64, v2
	v_xor_b32_e32 v48, 32, v46
	v_xor_b32_e32 v49, 16, v46
	v_xor_b32_e32 v50, 8, v46
	v_xor_b32_e32 v51, 4, v46
	v_xor_b32_e32 v52, 2, v46
	v_xor_b32_e32 v53, 1, v46
	v_lshlrev_b32_e32 v36, 2, v34
	v_mov_b32_e32 v54, 0x42000000
	v_mov_b32_e32 v55, 0x64
	v_mov_b32_e32 v56, 0x16e48000
	v_mov_b32_e32 v57, 0x16e38000
	v_mov_b32_e32 v58, 0x4538000
	v_mov_b32_e32 v59, 0x2538000
	s_branch .LBB0_964

; __global__ void __launch_bounds__(256, 2) mega(Params p) {
;   extern __shared__ __attribute__((aligned(16))) char smem[];
	.amdhsa_kernel _Z4mega6Params
		.amdhsa_group_segment_fixed_size 0
		.amdhsa_private_segment_fixed_size 0
		.amdhsa_kernarg_size 448
		.amdhsa_user_sgpr_count 2
		.amdhsa_user_sgpr_dispatch_ptr 0
		.amdhsa_user_sgpr_queue_ptr 0
		.amdhsa_user_sgpr_kernarg_segment_ptr 1
		.amdhsa_user_sgpr_dispatch_id 0
		.amdhsa_user_sgpr_kernarg_preload_length 0
		.amdhsa_user_sgpr_kernarg_preload_offset 0
		.amdhsa_user_sgpr_private_segment_size 0
		.amdhsa_uses_dynamic_stack 0
		.amdhsa_enable_private_segment 0
		.amdhsa_system_sgpr_workgroup_id_x 1
		.amdhsa_system_sgpr_workgroup_id_y 0
		.amdhsa_system_sgpr_workgroup_id_z 0
		.amdhsa_system_sgpr_workgroup_info 0
		.amdhsa_system_vgpr_workitem_id 0
		.amdhsa_next_free_vgpr 246
		.amdhsa_next_free_sgpr 100
		.amdhsa_accum_offset 248
		.amdhsa_reserve_vcc 1
		.amdhsa_float_round_mode_32 0
		.amdhsa_float_round_mode_16_64 0
		.amdhsa_float_denorm_mode_32 3
		.amdhsa_float_denorm_mode_16_64 3
		.amdhsa_dx10_clamp 1
		.amdhsa_ieee_mode 1
		.amdhsa_fp16_overflow 0
		.amdhsa_tg_split 0
		.amdhsa_exception_fp_ieee_invalid_op 0
		.amdhsa_exception_fp_denorm_src 0
		.amdhsa_exception_fp_ieee_div_zero 0
		.amdhsa_exception_fp_ieee_overflow 0
		.amdhsa_exception_fp_ieee_underflow 0
		.amdhsa_exception_fp_ieee_inexact 0
		.amdhsa_exception_int_div_zero 0
	.end_amdhsa_kernel
